# as DAB + D loops: waves 0-3 take the tile barrier before their last 4 P.V MFMAs and issue their DMAs under them
# speedup vs baseline: 1.0274x; 1.0054x over previous
; #define SBAR() __builtin_amdgcn_sched_barrier(0)
; template <int D0> __device__ __forceinline__ void pv_one(f32x16& od, int vb, bf16x8 pa0, bf16x8 pa1, bf16x8 pa2, bf16x8 pa3) {
;     const s16x4 l0 = tr_read<v_rd_off(D0, 0, 0)>(vb), h0 = tr_read<v_rd_off(D0, 0, 1)>(vb), l1 = tr_read<v_rd_off(D0, 1, 0)>(vb), h1 = tr_read<v_rd_off(D0, 1, 1)>(vb);
;     const s16x4 l2 = tr_read<v_rd_off(D0, 2, 0)>(vb), h2 = tr_read<v_rd_off(D0, 2, 1)>(vb), l3 = tr_read<v_rd_off(D0, 3, 0)>(vb), h3 = tr_read<v_rd_off(D0, 3, 1)>(vb);
;     asm volatile("s_waitcnt lgkmcnt(0)" ::: "memory"); SBAR();
;     ...
;     od = __builtin_amdgcn_mfma_f32_32x32x16_bf16(pa0, PK(l0, h0), od, 0, 0, 0);
;     od = __builtin_amdgcn_mfma_f32_32x32x16_bf16(pa1, PK(l1, h1), od, 0, 0, 0);
;     od = __builtin_amdgcn_mfma_f32_32x32x16_bf16(pa2, PK(l2, h2), od, 0, 0, 0);
;     od = __builtin_amdgcn_mfma_f32_32x32x16_bf16(pa3, PK(l3, h3), od, 0, 0, 0);
;     ...
; }
; template <bool RSM> __device__ __forceinline__ void pv_d0(f32x16* o, f32x16& lacc, int vb, bf16x8 pa0, bf16x8 pa1, bf16x8 pa2, bf16x8 pa3) {
;     if (RSM) {
;         const bf16x8 ones = {0x3F80, 0x3F80, 0x3F80, 0x3F80, 0x3F80, 0x3F80, 0x3F80, 0x3F80};
;         lacc = __builtin_amdgcn_mfma_f32_32x32x16_bf16(pa0, ones, lacc, 0, 0, 0);
;         lacc = __builtin_amdgcn_mfma_f32_32x32x16_bf16(pa1, ones, lacc, 0, 0, 0);
;         lacc = __builtin_amdgcn_mfma_f32_32x32x16_bf16(pa2, ones, lacc, 0, 0, 0);
;         lacc = __builtin_amdgcn_mfma_f32_32x32x16_bf16(pa3, ones, lacc, 0, 0, 0); }
;     pv_one<0>(o[0], vb, pa0, pa1, pa2, pa3); pv_one<1>(o[1], vb, pa0, pa1, pa2, pa3); pv_one<2>(o[2], vb, pa0, pa1, pa2, pa3); pv_one<3>(o[3], vb, pa0, pa1, pa2, pa3);
; }
.LBB0_704:
	s_mov_b32 s38, s36
	s_mov_b32 s39, s36
	s_mov_b32 s37, s36
	v_mov_b64_e32 v[134:135], s[38:39]
	v_mov_b64_e32 v[132:133], s[36:37]
	s_lshl_b32 s23, s35, 14
	v_add_u32_e32 v0, s23, v230
	v_mfma_f32_32x32x16_bf16 v[96:111], v[6:9], v[132:135], v[96:111]
	ds_read_b64_tr_b16 v[136:137], v0 offset:0
	ds_read_b64_tr_b16 v[138:139], v0 offset:0x800
	ds_read_b64_tr_b16 v[140:141], v0 offset:0x1000
	ds_read_b64_tr_b16 v[142:143], v0 offset:0x1800
	ds_read_b64_tr_b16 v[192:193], v0 offset:0x2000
	ds_read_b64_tr_b16 v[194:195], v0 offset:0x2800
	ds_read_b64_tr_b16 v[196:197], v0 offset:0x3000
	v_mfma_f32_32x32x16_bf16 v[96:111], v[2:5], v[132:135], v[96:111]
	ds_read_b64_tr_b16 v[198:199], v0 offset:0x3800
	s_waitcnt lgkmcnt(0)
	v_mfma_f32_32x32x16_bf16 v[96:111], v[128:131], v[132:135], v[96:111]
	v_mfma_f32_32x32x16_bf16 v[96:111], v[10:13], v[132:135], v[96:111]
	v_mfma_f32_32x32x16_bf16 v[80:95], v[6:9], v[136:139], v[80:95]
	ds_read_b64_tr_b16 v[132:133], v0 offset:0x200
	ds_read_b64_tr_b16 v[134:135], v0 offset:0xa00
	ds_read_b64_tr_b16 v[136:137], v0 offset:0x1200
	ds_read_b64_tr_b16 v[138:139], v0 offset:0x1a00
	v_mfma_f32_32x32x16_bf16 v[80:95], v[2:5], v[140:143], v[80:95]
	ds_read_b64_tr_b16 v[140:141], v0 offset:0x2200
	ds_read_b64_tr_b16 v[142:143], v0 offset:0x2a00
	v_mfma_f32_32x32x16_bf16 v[80:95], v[128:131], v[192:195], v[80:95]
	ds_read_b64_tr_b16 v[192:193], v0 offset:0x3200
	ds_read_b64_tr_b16 v[194:195], v0 offset:0x3a00
	s_waitcnt lgkmcnt(0)
	v_mfma_f32_32x32x16_bf16 v[80:95], v[10:13], v[196:199], v[80:95]
	v_mfma_f32_32x32x16_bf16 v[64:79], v[6:9], v[132:135], v[64:79]
	ds_read_b64_tr_b16 v[132:133], v0 offset:0x400
	ds_read_b64_tr_b16 v[134:135], v0 offset:0xc00
	v_mfma_f32_32x32x16_bf16 v[64:79], v[2:5], v[136:139], v[64:79]
	ds_read_b64_tr_b16 v[136:137], v0 offset:0x1400
	ds_read_b64_tr_b16 v[138:139], v0 offset:0x1c00
	v_mfma_f32_32x32x16_bf16 v[64:79], v[128:131], v[140:143], v[64:79]
	ds_read_b64_tr_b16 v[140:141], v0 offset:0x2400
	ds_read_b64_tr_b16 v[142:143], v0 offset:0x2c00
	v_mfma_f32_32x32x16_bf16 v[64:79], v[10:13], v[192:195], v[64:79]
	ds_read_b64_tr_b16 v[192:193], v0 offset:0x3400
	ds_read_b64_tr_b16 v[194:195], v0 offset:0x3c00
	s_waitcnt lgkmcnt(0)
	v_mfma_f32_32x32x16_bf16 v[48:63], v[6:9], v[132:135], v[48:63]
	ds_read_b64_tr_b16 v[132:133], v0 offset:0x600
	ds_read_b64_tr_b16 v[134:135], v0 offset:0xe00
	v_mfma_f32_32x32x16_bf16 v[48:63], v[2:5], v[136:139], v[48:63]
	ds_read_b64_tr_b16 v[136:137], v0 offset:0x1600
	ds_read_b64_tr_b16 v[138:139], v0 offset:0x1e00
	v_mfma_f32_32x32x16_bf16 v[48:63], v[128:131], v[140:143], v[48:63]
	ds_read_b64_tr_b16 v[140:141], v0 offset:0x2600
	ds_read_b64_tr_b16 v[142:143], v0 offset:0x2e00
	v_mfma_f32_32x32x16_bf16 v[48:63], v[10:13], v[192:195], v[48:63]
	ds_read_b64_tr_b16 v[192:193], v0 offset:0x3600
	ds_read_b64_tr_b16 v[194:195], v0 offset:0x3e00
	s_waitcnt lgkmcnt(0)
	s_and_b64 vcc, exec, s[0:1]
	s_cbranch_vccnz .Lmy_slow_0
	s_cmpk_gt_u32 s57, 0xfc
	s_cbranch_scc1 .Lmy_slow_0
	s_mov_b64 s[20:21], -1
	s_add_i32 m0, s81, s22
	s_addk_i32 s23, 0xc000
	s_cmp_gt_i32 s35, 0
	s_cselect_b32 s20, s23, 0xc000
	s_waitcnt vmcnt(3) lgkmcnt(0)
	s_barrier
	v_mfma_f32_32x32x16_bf16 v[32:47], v[6:9], v[132:135], v[32:47]
	s_and_b64 vcc, exec, s[0:1]
	v_mfma_f32_32x32x16_bf16 v[32:47], v[2:5], v[136:139], v[32:47]
	v_mfma_f32_32x32x16_bf16 v[32:47], v[128:131], v[140:143], v[32:47]
	v_mfma_f32_32x32x16_bf16 v[32:47], v[10:13], v[192:195], v[32:47]
	s_add_i32 s20, s63, s20
	global_load_lds_dwordx4 v[214:215], off
	s_mov_b32 m0, s20
	v_lshl_add_u64 v[214:215], v[214:215], 0, s[74:75]
	global_load_lds_dwordx4 v[212:213], off
	s_add_i32 m0, s20, 0x2000
	v_lshl_add_u64 v[2:3], v[212:213], 0, s[74:75]
	global_load_lds_dwordx4 v[216:217], off
	v_lshl_add_u64 v[4:5], v[216:217], 0, s[74:75]
	v_mov_b64_e32 v[216:217], v[4:5]
	v_mov_b64_e32 v[212:213], v[2:3]
	s_branch .LBB0_709
.Lmy_slow_0:
	v_mfma_f32_32x32x16_bf16 v[32:47], v[6:9], v[132:135], v[32:47]
	s_and_b64 vcc, exec, s[0:1]
	v_mfma_f32_32x32x16_bf16 v[32:47], v[2:5], v[136:139], v[32:47]
	v_mfma_f32_32x32x16_bf16 v[32:47], v[128:131], v[140:143], v[32:47]
	v_mfma_f32_32x32x16_bf16 v[32:47], v[10:13], v[192:195], v[32:47]
	s_cbranch_vccnz .LBB0_709

; #define SBAR() __builtin_amdgcn_sched_barrier(0)
; template <int D0> __device__ __forceinline__ void pv_one(f32x16& od, int vb, bf16x8 pa0, bf16x8 pa1, bf16x8 pa2, bf16x8 pa3) {
;     const s16x4 l0 = tr_read<v_rd_off(D0, 0, 0)>(vb), h0 = tr_read<v_rd_off(D0, 0, 1)>(vb), l1 = tr_read<v_rd_off(D0, 1, 0)>(vb), h1 = tr_read<v_rd_off(D0, 1, 1)>(vb);
;     const s16x4 l2 = tr_read<v_rd_off(D0, 2, 0)>(vb), h2 = tr_read<v_rd_off(D0, 2, 1)>(vb), l3 = tr_read<v_rd_off(D0, 3, 0)>(vb), h3 = tr_read<v_rd_off(D0, 3, 1)>(vb);
;     asm volatile("s_waitcnt lgkmcnt(0)" ::: "memory"); SBAR();
;     ...
;     od = __builtin_amdgcn_mfma_f32_32x32x16_bf16(pa0, PK(l0, h0), od, 0, 0, 0);
;     od = __builtin_amdgcn_mfma_f32_32x32x16_bf16(pa1, PK(l1, h1), od, 0, 0, 0);
;     od = __builtin_amdgcn_mfma_f32_32x32x16_bf16(pa2, PK(l2, h2), od, 0, 0, 0);
;     od = __builtin_amdgcn_mfma_f32_32x32x16_bf16(pa3, PK(l3, h3), od, 0, 0, 0);
;     ...
; }
; template <bool RSM> __device__ __forceinline__ void pv_d0(f32x16* o, f32x16& lacc, int vb, bf16x8 pa0, bf16x8 pa1, bf16x8 pa2, bf16x8 pa3) {
;     if (RSM) {
;         const bf16x8 ones = {0x3F80, 0x3F80, 0x3F80, 0x3F80, 0x3F80, 0x3F80, 0x3F80, 0x3F80};
;         lacc = __builtin_amdgcn_mfma_f32_32x32x16_bf16(pa0, ones, lacc, 0, 0, 0);
;         lacc = __builtin_amdgcn_mfma_f32_32x32x16_bf16(pa1, ones, lacc, 0, 0, 0);
;         lacc = __builtin_amdgcn_mfma_f32_32x32x16_bf16(pa2, ones, lacc, 0, 0, 0);
;         lacc = __builtin_amdgcn_mfma_f32_32x32x16_bf16(pa3, ones, lacc, 0, 0, 0); }
;     pv_one<0>(o[0], vb, pa0, pa1, pa2, pa3); pv_one<1>(o[1], vb, pa0, pa1, pa2, pa3); pv_one<2>(o[2], vb, pa0, pa1, pa2, pa3); pv_one<3>(o[3], vb, pa0, pa1, pa2, pa3);
; }
.LBB0_719:
	s_mov_b32 s38, s36
	s_mov_b32 s39, s36
	s_mov_b32 s37, s36
	v_mov_b64_e32 v[150:151], s[38:39]
	v_mov_b64_e32 v[148:149], s[36:37]
	s_lshl_b32 s37, s35, 14
	v_add_u32_e32 v14, s37, v230
	v_mfma_f32_32x32x16_bf16 v[96:111], v[6:9], v[148:151], v[96:111]
	ds_read_b64_tr_b16 v[152:153], v14 offset:0
	ds_read_b64_tr_b16 v[154:155], v14 offset:0x800
	ds_read_b64_tr_b16 v[156:157], v14 offset:0x1000
	ds_read_b64_tr_b16 v[158:159], v14 offset:0x1800
	ds_read_b64_tr_b16 v[192:193], v14 offset:0x2000
	ds_read_b64_tr_b16 v[194:195], v14 offset:0x2800
	ds_read_b64_tr_b16 v[196:197], v14 offset:0x3000
	v_mfma_f32_32x32x16_bf16 v[96:111], v[2:5], v[148:151], v[96:111]
	ds_read_b64_tr_b16 v[198:199], v14 offset:0x3800
	s_waitcnt lgkmcnt(0)
	v_mfma_f32_32x32x16_bf16 v[96:111], v[144:147], v[148:151], v[96:111]
	v_mfma_f32_32x32x16_bf16 v[96:111], v[10:13], v[148:151], v[96:111]
	v_mfma_f32_32x32x16_bf16 v[80:95], v[6:9], v[152:155], v[80:95]
	ds_read_b64_tr_b16 v[148:149], v14 offset:0x200
	ds_read_b64_tr_b16 v[150:151], v14 offset:0xa00
	ds_read_b64_tr_b16 v[152:153], v14 offset:0x1200
	ds_read_b64_tr_b16 v[154:155], v14 offset:0x1a00
	v_mfma_f32_32x32x16_bf16 v[80:95], v[2:5], v[156:159], v[80:95]
	ds_read_b64_tr_b16 v[156:157], v14 offset:0x2200
	ds_read_b64_tr_b16 v[158:159], v14 offset:0x2a00
	v_mfma_f32_32x32x16_bf16 v[80:95], v[144:147], v[192:195], v[80:95]
	ds_read_b64_tr_b16 v[192:193], v14 offset:0x3200
	ds_read_b64_tr_b16 v[194:195], v14 offset:0x3a00
	s_waitcnt lgkmcnt(0)
	v_mfma_f32_32x32x16_bf16 v[80:95], v[10:13], v[196:199], v[80:95]
	v_mfma_f32_32x32x16_bf16 v[64:79], v[6:9], v[148:151], v[64:79]
	ds_read_b64_tr_b16 v[148:149], v14 offset:0x400
	ds_read_b64_tr_b16 v[150:151], v14 offset:0xc00
	v_mfma_f32_32x32x16_bf16 v[64:79], v[2:5], v[152:155], v[64:79]
	ds_read_b64_tr_b16 v[152:153], v14 offset:0x1400
	ds_read_b64_tr_b16 v[154:155], v14 offset:0x1c00
	v_mfma_f32_32x32x16_bf16 v[64:79], v[144:147], v[156:159], v[64:79]
	ds_read_b64_tr_b16 v[156:157], v14 offset:0x2400
	ds_read_b64_tr_b16 v[158:159], v14 offset:0x2c00
	v_mfma_f32_32x32x16_bf16 v[64:79], v[10:13], v[192:195], v[64:79]
	ds_read_b64_tr_b16 v[192:193], v14 offset:0x3400
	ds_read_b64_tr_b16 v[194:195], v14 offset:0x3c00
	s_waitcnt lgkmcnt(0)
	v_mfma_f32_32x32x16_bf16 v[48:63], v[6:9], v[148:151], v[48:63]
	ds_read_b64_tr_b16 v[148:149], v14 offset:0x600
	ds_read_b64_tr_b16 v[150:151], v14 offset:0xe00
	v_mfma_f32_32x32x16_bf16 v[48:63], v[2:5], v[152:155], v[48:63]
	ds_read_b64_tr_b16 v[152:153], v14 offset:0x1600
	ds_read_b64_tr_b16 v[154:155], v14 offset:0x1e00
	v_mfma_f32_32x32x16_bf16 v[48:63], v[144:147], v[156:159], v[48:63]
	ds_read_b64_tr_b16 v[156:157], v14 offset:0x2600
	ds_read_b64_tr_b16 v[158:159], v14 offset:0x2e00
	v_mfma_f32_32x32x16_bf16 v[48:63], v[10:13], v[192:195], v[48:63]
	ds_read_b64_tr_b16 v[192:193], v14 offset:0x3600
	ds_read_b64_tr_b16 v[194:195], v14 offset:0x3e00
	s_waitcnt lgkmcnt(0)
	s_and_b64 vcc, exec, s[0:1]
	s_cbranch_vccnz .Lmy_slow_1
	s_cmpk_gt_u32 s57, 0xfb
	s_cbranch_scc1 .Lmy_slow_1
	s_mov_b64 s[22:23], -1
	s_add_i32 m0, s81, s78
	s_addk_i32 s37, 0xc000
	s_cmp_gt_i32 s35, 0
	s_cselect_b32 s22, s37, 0xc000
	s_waitcnt vmcnt(3) lgkmcnt(0)
	s_barrier
	v_mfma_f32_32x32x16_bf16 v[32:47], v[6:9], v[148:151], v[32:47]
	s_and_b64 vcc, exec, s[0:1]
	v_mfma_f32_32x32x16_bf16 v[32:47], v[2:5], v[152:155], v[32:47]
	v_mfma_f32_32x32x16_bf16 v[32:47], v[144:147], v[156:159], v[32:47]
	v_mfma_f32_32x32x16_bf16 v[32:47], v[10:13], v[192:195], v[32:47]
	s_add_i32 s22, s63, s22
	global_load_lds_dwordx4 v[214:215], off
	s_mov_b32 m0, s22
	v_lshl_add_u64 v[214:215], v[214:215], 0, s[74:75]
	global_load_lds_dwordx4 v[212:213], off
	s_add_i32 m0, s22, 0x2000
	v_lshl_add_u64 v[2:3], v[212:213], 0, s[74:75]
	global_load_lds_dwordx4 v[216:217], off
	v_lshl_add_u64 v[4:5], v[216:217], 0, s[74:75]
	v_mov_b64_e32 v[216:217], v[4:5]
	v_mov_b64_e32 v[212:213], v[2:3]
	s_branch .LBB0_724
.Lmy_slow_1:
	v_mfma_f32_32x32x16_bf16 v[32:47], v[6:9], v[148:151], v[32:47]
	s_and_b64 vcc, exec, s[0:1]
	v_mfma_f32_32x32x16_bf16 v[32:47], v[2:5], v[152:155], v[32:47]
	v_mfma_f32_32x32x16_bf16 v[32:47], v[144:147], v[156:159], v[32:47]
	v_mfma_f32_32x32x16_bf16 v[32:47], v[10:13], v[192:195], v[32:47]
	s_cbranch_vccnz .LBB0_724

; #define SBAR() __builtin_amdgcn_sched_barrier(0)
; template <int D0> __device__ __forceinline__ void pv_one(f32x16& od, int vb, bf16x8 pa0, bf16x8 pa1, bf16x8 pa2, bf16x8 pa3) {
;     const s16x4 l0 = tr_read<v_rd_off(D0, 0, 0)>(vb), h0 = tr_read<v_rd_off(D0, 0, 1)>(vb), l1 = tr_read<v_rd_off(D0, 1, 0)>(vb), h1 = tr_read<v_rd_off(D0, 1, 1)>(vb);
;     const s16x4 l2 = tr_read<v_rd_off(D0, 2, 0)>(vb), h2 = tr_read<v_rd_off(D0, 2, 1)>(vb), l3 = tr_read<v_rd_off(D0, 3, 0)>(vb), h3 = tr_read<v_rd_off(D0, 3, 1)>(vb);
;     asm volatile("s_waitcnt lgkmcnt(0)" ::: "memory"); SBAR();
;     ...
;     od = __builtin_amdgcn_mfma_f32_32x32x16_bf16(pa0, PK(l0, h0), od, 0, 0, 0);
;     od = __builtin_amdgcn_mfma_f32_32x32x16_bf16(pa1, PK(l1, h1), od, 0, 0, 0);
;     od = __builtin_amdgcn_mfma_f32_32x32x16_bf16(pa2, PK(l2, h2), od, 0, 0, 0);
;     od = __builtin_amdgcn_mfma_f32_32x32x16_bf16(pa3, PK(l3, h3), od, 0, 0, 0);
;     ...
; }
; template <bool RSM> __device__ __forceinline__ void pv_d0(f32x16* o, f32x16& lacc, int vb, bf16x8 pa0, bf16x8 pa1, bf16x8 pa2, bf16x8 pa3) {
;     if (RSM) {
;         const bf16x8 ones = {0x3F80, 0x3F80, 0x3F80, 0x3F80, 0x3F80, 0x3F80, 0x3F80, 0x3F80};
;         lacc = __builtin_amdgcn_mfma_f32_32x32x16_bf16(pa0, ones, lacc, 0, 0, 0);
;         lacc = __builtin_amdgcn_mfma_f32_32x32x16_bf16(pa1, ones, lacc, 0, 0, 0);
;         lacc = __builtin_amdgcn_mfma_f32_32x32x16_bf16(pa2, ones, lacc, 0, 0, 0);
;         lacc = __builtin_amdgcn_mfma_f32_32x32x16_bf16(pa3, ones, lacc, 0, 0, 0); }
;     pv_one<0>(o[0], vb, pa0, pa1, pa2, pa3); pv_one<1>(o[1], vb, pa0, pa1, pa2, pa3); pv_one<2>(o[2], vb, pa0, pa1, pa2, pa3); pv_one<3>(o[3], vb, pa0, pa1, pa2, pa3);
; }
.LBB0_779:
	s_mov_b32 s38, s36
	s_mov_b32 s39, s36
	s_mov_b32 s37, s36
	v_mov_b64_e32 v[118:119], s[38:39]
	v_mov_b64_e32 v[116:117], s[36:37]
	s_lshl_b32 s15, s18, 14
	v_add_u32_e32 v0, s15, v192
	v_mfma_f32_32x32x16_bf16 v[80:95], v[6:9], v[116:119], v[80:95]
	ds_read_b64_tr_b16 v[120:121], v0 offset:0
	ds_read_b64_tr_b16 v[122:123], v0 offset:0x800
	ds_read_b64_tr_b16 v[124:125], v0 offset:0x1000
	ds_read_b64_tr_b16 v[126:127], v0 offset:0x1800
	ds_read_b64_tr_b16 v[176:177], v0 offset:0x2000
	ds_read_b64_tr_b16 v[178:179], v0 offset:0x2800
	ds_read_b64_tr_b16 v[180:181], v0 offset:0x3000
	v_mfma_f32_32x32x16_bf16 v[80:95], v[2:5], v[116:119], v[80:95]
	ds_read_b64_tr_b16 v[182:183], v0 offset:0x3800
	s_waitcnt lgkmcnt(0)
	v_mfma_f32_32x32x16_bf16 v[80:95], v[112:115], v[116:119], v[80:95]
	v_mfma_f32_32x32x16_bf16 v[80:95], v[10:13], v[116:119], v[80:95]
	v_mfma_f32_32x32x16_bf16 v[64:79], v[6:9], v[120:123], v[64:79]
	ds_read_b64_tr_b16 v[116:117], v0 offset:0x200
	ds_read_b64_tr_b16 v[118:119], v0 offset:0xa00
	ds_read_b64_tr_b16 v[120:121], v0 offset:0x1200
	ds_read_b64_tr_b16 v[122:123], v0 offset:0x1a00
	v_mfma_f32_32x32x16_bf16 v[64:79], v[2:5], v[124:127], v[64:79]
	ds_read_b64_tr_b16 v[124:125], v0 offset:0x2200
	ds_read_b64_tr_b16 v[126:127], v0 offset:0x2a00
	v_mfma_f32_32x32x16_bf16 v[64:79], v[112:115], v[176:179], v[64:79]
	ds_read_b64_tr_b16 v[176:177], v0 offset:0x3200
	ds_read_b64_tr_b16 v[178:179], v0 offset:0x3a00
	s_waitcnt lgkmcnt(0)
	v_mfma_f32_32x32x16_bf16 v[64:79], v[10:13], v[180:183], v[64:79]
	v_mfma_f32_32x32x16_bf16 v[48:63], v[6:9], v[116:119], v[48:63]
	ds_read_b64_tr_b16 v[116:117], v0 offset:0x400
	ds_read_b64_tr_b16 v[118:119], v0 offset:0xc00
	v_mfma_f32_32x32x16_bf16 v[48:63], v[2:5], v[120:123], v[48:63]
	ds_read_b64_tr_b16 v[120:121], v0 offset:0x1400
	ds_read_b64_tr_b16 v[122:123], v0 offset:0x1c00
	v_mfma_f32_32x32x16_bf16 v[48:63], v[112:115], v[124:127], v[48:63]
	ds_read_b64_tr_b16 v[124:125], v0 offset:0x2400
	ds_read_b64_tr_b16 v[126:127], v0 offset:0x2c00
	v_mfma_f32_32x32x16_bf16 v[48:63], v[10:13], v[176:179], v[48:63]
	ds_read_b64_tr_b16 v[176:177], v0 offset:0x3400
	ds_read_b64_tr_b16 v[178:179], v0 offset:0x3c00
	s_waitcnt lgkmcnt(0)
	v_mfma_f32_32x32x16_bf16 v[32:47], v[6:9], v[116:119], v[32:47]
	ds_read_b64_tr_b16 v[116:117], v0 offset:0x600
	ds_read_b64_tr_b16 v[118:119], v0 offset:0xe00
	v_mfma_f32_32x32x16_bf16 v[32:47], v[2:5], v[120:123], v[32:47]
	ds_read_b64_tr_b16 v[120:121], v0 offset:0x1600
	ds_read_b64_tr_b16 v[122:123], v0 offset:0x1e00
	v_mfma_f32_32x32x16_bf16 v[32:47], v[112:115], v[124:127], v[32:47]
	ds_read_b64_tr_b16 v[124:125], v0 offset:0x2600
	ds_read_b64_tr_b16 v[126:127], v0 offset:0x2e00
	v_mfma_f32_32x32x16_bf16 v[32:47], v[10:13], v[176:179], v[32:47]
	ds_read_b64_tr_b16 v[176:177], v0 offset:0x3600
	ds_read_b64_tr_b16 v[178:179], v0 offset:0x3e00
	s_waitcnt lgkmcnt(0)
	s_and_b64 vcc, exec, s[0:1]
	s_cbranch_vccnz .Lmy_slow_2
	s_cmpk_gt_u32 s17, 0xfc
	s_cbranch_scc1 .Lmy_slow_2
	s_mov_b64 s[12:13], -1
	s_add_i32 m0, s81, s14
	s_addk_i32 s15, 0xc000
	s_cmp_gt_i32 s18, 0
	s_cselect_b32 s12, s15, 0xc000
	s_waitcnt vmcnt(3) lgkmcnt(0)
	s_barrier
	v_mfma_f32_32x32x16_bf16 v[16:31], v[6:9], v[116:119], v[16:31]
	s_and_b64 vcc, exec, s[0:1]
	v_mfma_f32_32x32x16_bf16 v[16:31], v[2:5], v[120:123], v[16:31]
	v_mfma_f32_32x32x16_bf16 v[16:31], v[112:115], v[124:127], v[16:31]
	v_mfma_f32_32x32x16_bf16 v[16:31], v[10:13], v[176:179], v[16:31]
	s_add_i32 s12, s63, s12
	global_load_lds_dwordx4 v[184:185], off
	s_mov_b32 m0, s12
	v_lshl_add_u64 v[184:185], v[184:185], 0, s[74:75]
	global_load_lds_dwordx4 v[186:187], off
	s_add_i32 m0, s12, 0x2000
	v_lshl_add_u64 v[2:3], v[186:187], 0, s[74:75]
	global_load_lds_dwordx4 v[188:189], off
	v_lshl_add_u64 v[4:5], v[188:189], 0, s[74:75]
	v_mov_b64_e32 v[188:189], v[4:5]
	v_mov_b64_e32 v[186:187], v[2:3]
	s_branch .LBB0_784
.Lmy_slow_2:
	v_mfma_f32_32x32x16_bf16 v[16:31], v[6:9], v[116:119], v[16:31]
	s_and_b64 vcc, exec, s[0:1]
	v_mfma_f32_32x32x16_bf16 v[16:31], v[2:5], v[120:123], v[16:31]
	v_mfma_f32_32x32x16_bf16 v[16:31], v[112:115], v[124:127], v[16:31]
	v_mfma_f32_32x32x16_bf16 v[16:31], v[10:13], v[176:179], v[16:31]
	s_cbranch_vccnz .LBB0_784

; #define SBAR() __builtin_amdgcn_sched_barrier(0)
; template <int D0> __device__ __forceinline__ void pv_one(f32x16& od, int vb, bf16x8 pa0, bf16x8 pa1, bf16x8 pa2, bf16x8 pa3) {
;     const s16x4 l0 = tr_read<v_rd_off(D0, 0, 0)>(vb), h0 = tr_read<v_rd_off(D0, 0, 1)>(vb), l1 = tr_read<v_rd_off(D0, 1, 0)>(vb), h1 = tr_read<v_rd_off(D0, 1, 1)>(vb);
;     const s16x4 l2 = tr_read<v_rd_off(D0, 2, 0)>(vb), h2 = tr_read<v_rd_off(D0, 2, 1)>(vb), l3 = tr_read<v_rd_off(D0, 3, 0)>(vb), h3 = tr_read<v_rd_off(D0, 3, 1)>(vb);
;     asm volatile("s_waitcnt lgkmcnt(0)" ::: "memory"); SBAR();
;     ...
;     od = __builtin_amdgcn_mfma_f32_32x32x16_bf16(pa0, PK(l0, h0), od, 0, 0, 0);
;     od = __builtin_amdgcn_mfma_f32_32x32x16_bf16(pa1, PK(l1, h1), od, 0, 0, 0);
;     od = __builtin_amdgcn_mfma_f32_32x32x16_bf16(pa2, PK(l2, h2), od, 0, 0, 0);
;     od = __builtin_amdgcn_mfma_f32_32x32x16_bf16(pa3, PK(l3, h3), od, 0, 0, 0);
;     ...
; }
; template <bool RSM> __device__ __forceinline__ void pv_d0(f32x16* o, f32x16& lacc, int vb, bf16x8 pa0, bf16x8 pa1, bf16x8 pa2, bf16x8 pa3) {
;     if (RSM) {
;         const bf16x8 ones = {0x3F80, 0x3F80, 0x3F80, 0x3F80, 0x3F80, 0x3F80, 0x3F80, 0x3F80};
;         lacc = __builtin_amdgcn_mfma_f32_32x32x16_bf16(pa0, ones, lacc, 0, 0, 0);
;         lacc = __builtin_amdgcn_mfma_f32_32x32x16_bf16(pa1, ones, lacc, 0, 0, 0);
;         lacc = __builtin_amdgcn_mfma_f32_32x32x16_bf16(pa2, ones, lacc, 0, 0, 0);
;         lacc = __builtin_amdgcn_mfma_f32_32x32x16_bf16(pa3, ones, lacc, 0, 0, 0); }
;     pv_one<0>(o[0], vb, pa0, pa1, pa2, pa3); pv_one<1>(o[1], vb, pa0, pa1, pa2, pa3); pv_one<2>(o[2], vb, pa0, pa1, pa2, pa3); pv_one<3>(o[3], vb, pa0, pa1, pa2, pa3);
; }
.LBB0_794:
	s_mov_b32 s38, s36
	s_mov_b32 s39, s36
	s_mov_b32 s37, s36
	v_mov_b64_e32 v[134:135], s[38:39]
	v_mov_b64_e32 v[132:133], s[36:37]
	s_lshl_b32 s31, s18, 14
	v_add_u32_e32 v14, s31, v192
	v_mfma_f32_32x32x16_bf16 v[80:95], v[6:9], v[132:135], v[80:95]
	ds_read_b64_tr_b16 v[136:137], v14 offset:0
	ds_read_b64_tr_b16 v[138:139], v14 offset:0x800
	ds_read_b64_tr_b16 v[140:141], v14 offset:0x1000
	ds_read_b64_tr_b16 v[142:143], v14 offset:0x1800
	ds_read_b64_tr_b16 v[176:177], v14 offset:0x2000
	ds_read_b64_tr_b16 v[178:179], v14 offset:0x2800
	ds_read_b64_tr_b16 v[180:181], v14 offset:0x3000
	v_mfma_f32_32x32x16_bf16 v[80:95], v[2:5], v[132:135], v[80:95]
	ds_read_b64_tr_b16 v[182:183], v14 offset:0x3800
	s_waitcnt lgkmcnt(0)
	v_mfma_f32_32x32x16_bf16 v[80:95], v[128:131], v[132:135], v[80:95]
	v_mfma_f32_32x32x16_bf16 v[80:95], v[10:13], v[132:135], v[80:95]
	v_mfma_f32_32x32x16_bf16 v[64:79], v[6:9], v[136:139], v[64:79]
	ds_read_b64_tr_b16 v[132:133], v14 offset:0x200
	ds_read_b64_tr_b16 v[134:135], v14 offset:0xa00
	ds_read_b64_tr_b16 v[136:137], v14 offset:0x1200
	ds_read_b64_tr_b16 v[138:139], v14 offset:0x1a00
	v_mfma_f32_32x32x16_bf16 v[64:79], v[2:5], v[140:143], v[64:79]
	ds_read_b64_tr_b16 v[140:141], v14 offset:0x2200
	ds_read_b64_tr_b16 v[142:143], v14 offset:0x2a00
	v_mfma_f32_32x32x16_bf16 v[64:79], v[128:131], v[176:179], v[64:79]
	ds_read_b64_tr_b16 v[176:177], v14 offset:0x3200
	ds_read_b64_tr_b16 v[178:179], v14 offset:0x3a00
	s_waitcnt lgkmcnt(0)
	v_mfma_f32_32x32x16_bf16 v[64:79], v[10:13], v[180:183], v[64:79]
	v_mfma_f32_32x32x16_bf16 v[48:63], v[6:9], v[132:135], v[48:63]
	ds_read_b64_tr_b16 v[132:133], v14 offset:0x400
	ds_read_b64_tr_b16 v[134:135], v14 offset:0xc00
	v_mfma_f32_32x32x16_bf16 v[48:63], v[2:5], v[136:139], v[48:63]
	ds_read_b64_tr_b16 v[136:137], v14 offset:0x1400
	ds_read_b64_tr_b16 v[138:139], v14 offset:0x1c00
	v_mfma_f32_32x32x16_bf16 v[48:63], v[128:131], v[140:143], v[48:63]
	ds_read_b64_tr_b16 v[140:141], v14 offset:0x2400
	ds_read_b64_tr_b16 v[142:143], v14 offset:0x2c00
	v_mfma_f32_32x32x16_bf16 v[48:63], v[10:13], v[176:179], v[48:63]
	ds_read_b64_tr_b16 v[176:177], v14 offset:0x3400
	ds_read_b64_tr_b16 v[178:179], v14 offset:0x3c00
	s_waitcnt lgkmcnt(0)
	v_mfma_f32_32x32x16_bf16 v[32:47], v[6:9], v[132:135], v[32:47]
	ds_read_b64_tr_b16 v[132:133], v14 offset:0x600
	ds_read_b64_tr_b16 v[134:135], v14 offset:0xe00
	v_mfma_f32_32x32x16_bf16 v[32:47], v[2:5], v[136:139], v[32:47]
	ds_read_b64_tr_b16 v[136:137], v14 offset:0x1600
	ds_read_b64_tr_b16 v[138:139], v14 offset:0x1e00
	v_mfma_f32_32x32x16_bf16 v[32:47], v[128:131], v[140:143], v[32:47]
	ds_read_b64_tr_b16 v[140:141], v14 offset:0x2600
	ds_read_b64_tr_b16 v[142:143], v14 offset:0x2e00
	v_mfma_f32_32x32x16_bf16 v[32:47], v[10:13], v[176:179], v[32:47]
	ds_read_b64_tr_b16 v[176:177], v14 offset:0x3600
	ds_read_b64_tr_b16 v[178:179], v14 offset:0x3e00
	s_waitcnt lgkmcnt(0)
	s_and_b64 vcc, exec, s[0:1]
	s_cbranch_vccnz .Lmy_slow_3
	s_cmpk_gt_u32 s17, 0xfb
	s_cbranch_scc1 .Lmy_slow_3
	s_mov_b64 s[14:15], -1
	s_add_i32 m0, s81, s26
	s_addk_i32 s31, 0xc000
	s_cmp_gt_i32 s18, 0
	s_cselect_b32 s14, s31, 0xc000
	s_waitcnt vmcnt(3) lgkmcnt(0)
	s_barrier
	v_mfma_f32_32x32x16_bf16 v[16:31], v[6:9], v[132:135], v[16:31]
	s_and_b64 vcc, exec, s[0:1]
	v_mfma_f32_32x32x16_bf16 v[16:31], v[2:5], v[136:139], v[16:31]
	v_mfma_f32_32x32x16_bf16 v[16:31], v[128:131], v[140:143], v[16:31]
	v_mfma_f32_32x32x16_bf16 v[16:31], v[10:13], v[176:179], v[16:31]
	s_add_i32 s14, s63, s14
	global_load_lds_dwordx4 v[184:185], off
	s_mov_b32 m0, s14
	v_lshl_add_u64 v[184:185], v[184:185], 0, s[74:75]
	global_load_lds_dwordx4 v[186:187], off
	s_add_i32 m0, s14, 0x2000
	v_lshl_add_u64 v[2:3], v[186:187], 0, s[74:75]
	global_load_lds_dwordx4 v[188:189], off
	v_lshl_add_u64 v[4:5], v[188:189], 0, s[74:75]
	v_mov_b64_e32 v[188:189], v[4:5]
	v_mov_b64_e32 v[186:187], v[2:3]
	s_branch .LBB0_799
.Lmy_slow_3:
	v_mfma_f32_32x32x16_bf16 v[16:31], v[6:9], v[132:135], v[16:31]
	s_and_b64 vcc, exec, s[0:1]
	v_mfma_f32_32x32x16_bf16 v[16:31], v[2:5], v[136:139], v[16:31]
	v_mfma_f32_32x32x16_bf16 v[16:31], v[128:131], v[140:143], v[16:31]
	v_mfma_f32_32x32x16_bf16 v[16:31], v[10:13], v[176:179], v[16:31]
	s_cbranch_vccnz .LBB0_799
